# P2b lru_unit<2>: four h_prev loads issued together earlier instead of a load/wait/store ladder
# baseline (speedup 1.0000x reference)
.LBB0_531:
	s_or_b64 exec, exec, s[28:29]
	v_ashrrev_i32_e32 v2, 2, v4
	v_and_b32_e32 v48, -16, v2
	v_and_b32_e32 v45, 15, v4
	v_add_u32_e32 v2, s6, v48
	v_or_b32_e32 v38, v2, v45
	v_ashrrev_i32_e32 v39, 31, v38
	v_bfe_u32 v44, v4, 4, 2
	v_lshlrev_b64 v[2:3], 8, v[38:39]
	v_readlane_b32 s72, v250, 7
	v_lshl_add_u64 v[4:5], s[14:15], 0, v[2:3]
	v_lshlrev_b32_e32 v36, 4, v44
	v_lshl_add_u64 v[2:3], s[24:25], 0, v[2:3]
	v_lshlrev_b64 v[40:41], 2, v[38:39]
	v_readlane_b32 s74, v250, 9
	v_readlane_b32 s75, v250, 10
	v_lshl_add_u64 v[4:5], v[4:5], 0, v[36:37]
	v_lshl_add_u64 v[6:7], v[2:3], 0, v[36:37]
	v_lshl_add_u64 v[46:47], s[70:71], 0, v[40:41]
	v_readlane_b32 s76, v250, 11
	v_readlane_b32 s77, v250, 12
	v_lshl_add_u64 v[50:51], s[74:75], 0, v[40:41]
	s_waitcnt lgkmcnt(0)
	s_barrier
	global_load_dwordx4 v[26:29], v[4:5], off
	global_load_dwordx4 v[30:33], v[6:7], off
	global_load_dwordx4 v[18:21], v[4:5], off offset:64
	global_load_dwordx4 v[22:25], v[6:7], off offset:64
	global_load_dwordx4 v[10:13], v[4:5], off offset:128
	global_load_dwordx4 v[14:17], v[6:7], off offset:128
	s_nop 0
	global_load_dwordx4 v[2:5], v[4:5], off offset:192
	s_nop 0
	global_load_dwordx4 v[6:9], v[6:7], off offset:192
	s_mov_b32 s6, 0xbfb8aa3b
	global_load_dword v46, v[46:47], off
	v_lshlrev_b32_e32 v48, 1, v48
	global_load_dword v47, v[50:51], off
	v_lshl_add_u64 v[50:51], s[76:77], 0, v[40:41]
	global_load_dword v49, v[50:51], off
	v_readlane_b32 s73, v250, 8
	v_readlane_b32 s78, v250, 13
	v_readlane_b32 s79, v250, 14
	v_readlane_b32 s80, v250, 15
	v_readlane_b32 s81, v250, 16
	v_readlane_b32 s82, v250, 17
	v_readlane_b32 s83, v250, 18
	v_readlane_b32 s84, v250, 19
	v_readlane_b32 s85, v250, 20
	v_readlane_b32 s86, v250, 21
	v_readlane_b32 s87, v250, 22
	v_readlane_b32 s72, v250, 51
	v_readlane_b32 s73, v250, 52
	v_readlane_b32 s74, v250, 53
	v_readlane_b32 s75, v250, 54
	v_readlane_b32 s76, v250, 55
	v_readlane_b32 s77, v250, 56
	v_readlane_b32 s78, v250, 57
	v_readlane_b32 s79, v250, 58
	v_readlane_b32 s80, v250, 59
	v_readlane_b32 s81, v250, 60
	v_readlane_b32 s82, v250, 61
	v_readlane_b32 s83, v250, 62
	v_readlane_b32 s84, v250, 63
	v_readlane_b32 s85, v249, 0
	s_mov_b64 s[72:73], s[76:77]
	s_mov_b64 s[74:75], s[78:79]
	s_add_i32 s34, s34, s94
	s_mov_b64 s[76:77], s[80:81]
	s_mov_b64 s[78:79], s[82:83]
	s_mov_b64 s[80:81], s[84:85]
	s_cmp_gt_i32 s34, 63
	v_readlane_b32 s86, v249, 1
	v_readlane_b32 s87, v249, 2
	s_waitcnt vmcnt(0)
	v_mul_f32_e32 v50, 0xbfb8aa3b, v49
	v_fma_f32 v51, v49, s6, -v50
	v_rndne_f32_e32 v52, v50
	v_fmac_f32_e32 v51, 0xb2a5705f, v49
	v_sub_f32_e32 v50, v50, v52
	v_add_f32_e32 v50, v50, v51
	v_exp_f32_e32 v50, v50
	v_cvt_i32_f32_e32 v51, v52
	s_mov_b32 s6, 0x42ce8ed0
	v_cmp_nlt_f32_e32 vcc, s6, v49
	s_mov_b32 s6, 0xc2b17218
	v_ldexp_f32 v50, v50, v51
	v_cndmask_b32_e32 v50, 0, v50, vcc
	v_cmp_ngt_f32_e32 vcc, s6, v49
	s_mov_b32 s6, 0x3f2aaaab
	s_nop 0
	v_cndmask_b32_e32 v49, v43, v50, vcc
	v_add_f32_e32 v52, 1.0, v49
	v_add_f32_e32 v50, -1.0, v52
	v_sub_f32_e32 v51, v50, v52
	v_add_f32_e32 v51, 1.0, v51
	v_sub_f32_e32 v50, v49, v50
	v_add_f32_e32 v53, v50, v51
	v_frexp_mant_f32_e32 v50, v52
	v_cmp_gt_f32_e32 vcc, s6, v50
	v_cvt_f64_f32_e32 v[50:51], v52
	v_frexp_exp_i32_f64_e32 v50, v[50:51]
	v_subbrev_co_u32_e32 v50, vcc, 0, v50, vcc
	v_sub_u32_e32 v51, 0, v50
	v_ldexp_f32 v52, v52, v51
	v_ldexp_f32 v51, v53, v51
	v_add_f32_e32 v53, -1.0, v52
	v_add_f32_e32 v54, 1.0, v53
	v_sub_f32_e32 v54, v52, v54
	v_add_f32_e32 v54, v51, v54
	v_add_f32_e32 v55, v53, v54
	v_sub_f32_e32 v53, v53, v55
	v_add_f32_e32 v53, v54, v53
	v_add_f32_e32 v54, 1.0, v52
	v_add_f32_e32 v56, -1.0, v54
	v_sub_f32_e32 v52, v52, v56
	v_add_f32_e32 v51, v51, v52
	v_add_f32_e32 v52, v54, v51
	v_sub_f32_e32 v54, v54, v52
	v_add_f32_e32 v51, v51, v54
	v_rcp_f32_e32 v54, v52
	v_cvt_f32_i32_e32 v50, v50
	s_mov_b32 s6, 0x3f317218
	v_mul_f32_e32 v56, v55, v54
	v_mul_f32_e32 v57, v52, v56
	v_fma_f32 v58, v56, v52, -v57
	v_fmac_f32_e32 v58, v56, v51
	v_add_f32_e32 v59, v57, v58
	v_sub_f32_e32 v60, v55, v59
	v_sub_f32_e32 v55, v55, v60
	v_sub_f32_e32 v57, v59, v57
	v_sub_f32_e32 v55, v55, v59
	v_add_f32_e32 v53, v53, v55
	v_sub_f32_e32 v55, v57, v58
	v_add_f32_e32 v53, v55, v53
	v_add_f32_e32 v55, v60, v53
	v_mul_f32_e32 v57, v54, v55
	v_mul_f32_e32 v58, v52, v57
	v_fma_f32 v52, v57, v52, -v58
	v_fmac_f32_e32 v52, v57, v51
	v_sub_f32_e32 v51, v60, v55
	v_add_f32_e32 v51, v53, v51
	v_add_f32_e32 v53, v58, v52
	v_sub_f32_e32 v59, v55, v53
	v_sub_f32_e32 v55, v55, v59
	v_sub_f32_e32 v58, v53, v58
	v_sub_f32_e32 v53, v55, v53
	v_add_f32_e32 v51, v51, v53
	v_sub_f32_e32 v52, v58, v52
	v_add_f32_e32 v51, v52, v51
	v_add_f32_e32 v52, v56, v57
	v_add_f32_e32 v51, v59, v51
	v_sub_f32_e32 v53, v52, v56
	v_mul_f32_e32 v51, v54, v51
	v_sub_f32_e32 v53, v57, v53
	v_add_f32_e32 v51, v53, v51
	v_mul_f32_e32 v56, 0x3f317218, v50
	v_add_f32_e32 v53, v52, v51
	v_fma_f32 v57, v50, s6, -v56
	v_mul_f32_e32 v54, v53, v53
	v_fmac_f32_e32 v57, 0xb102e308, v50
	v_sub_f32_e32 v50, v53, v52
	v_fmamk_f32 v55, v54, 0x3e9b6dac, v42
	v_sub_f32_e32 v50, v51, v50
	v_add_f32_e32 v51, v56, v57
	v_fmaak_f32 v55, v54, v55, 0x3f2aaada
	v_sub_f32_e32 v52, v51, v56
	v_ldexp_f32 v56, v53, 1
	v_mul_f32_e32 v53, v53, v54
	v_mul_f32_e32 v53, v53, v55
	v_add_f32_e32 v54, v56, v53
	v_sub_f32_e32 v55, v54, v56
	v_ldexp_f32 v50, v50, 1
	v_sub_f32_e32 v53, v53, v55
	v_add_f32_e32 v50, v50, v53
	v_add_f32_e32 v53, v54, v50
	v_sub_f32_e32 v54, v53, v54
	v_sub_f32_e32 v50, v50, v54
	v_add_f32_e32 v54, v51, v53
	v_sub_f32_e32 v55, v54, v51
	v_sub_f32_e32 v56, v54, v55
	v_sub_f32_e32 v52, v57, v52
	v_sub_f32_e32 v51, v51, v56
	v_sub_f32_e32 v53, v53, v55
	v_add_f32_e32 v51, v53, v51
	v_add_f32_e32 v53, v52, v50
	v_sub_f32_e32 v55, v53, v52
	v_sub_f32_e32 v56, v53, v55
	v_sub_f32_e32 v52, v52, v56
	v_sub_f32_e32 v50, v50, v55
	v_add_f32_e32 v51, v53, v51
	v_add_f32_e32 v50, v50, v52
	v_add_f32_e32 v52, v54, v51
	v_sub_f32_e32 v53, v52, v54
	v_sub_f32_e32 v51, v51, v53
	v_add_f32_e32 v50, v50, v51
	s_mov_b32 s6, 0x7f800000
	v_add_f32_e32 v50, v52, v50
	v_cmp_neq_f32_e32 vcc, s6, v49
	s_mov_b32 s6, 0x33800000
	s_nop 0
	v_cndmask_b32_e32 v50, v43, v50, vcc
	v_cmp_lt_f32_e64 vcc, |v49|, s6
	s_movk_i32 s6, 0x440
	s_nop 0
	v_cndmask_b32_e32 v49, v50, v49, vcc
	v_mul_u32_u24_e32 v50, 0x110, v45
	v_add3_u32 v54, 0, v36, v50
	ds_read_b128 v[50:53], v54
	s_waitcnt lgkmcnt(0)
	v_mfma_f32_16x16x32_bf16 v[26:29], v[50:53], v[26:29], 0
	v_mul_f32_e32 v49, 0xc1000000, v49
	v_lshlrev_b32_e32 v36, 2, v44
	v_or_b32_e32 v76, s5, v36
	v_ashrrev_i32_e32 v77, 31, v76
	v_lshlrev_b64 v[78:79], 12, v[76:77]
	v_lshl_add_u64 v[80:81], s[74:75], 0, v[40:41]
	v_lshl_add_u64 v[78:79], v[80:81], 0, v[78:79]
	v_mov_b32_e32 v84, 0x1000
	v_mov_b32_e32 v85, 0
	global_load_dword v72, v[78:79], off
	v_lshl_add_u64 v[78:79], v[78:79], 0, v[84:85]
	global_load_dword v73, v[78:79], off
	v_lshl_add_u64 v[78:79], v[78:79], 0, v[84:85]
	global_load_dword v74, v[78:79], off
	v_lshl_add_u64 v[78:79], v[78:79], 0, v[84:85]
	global_load_dword v75, v[78:79], off
	v_mfma_f32_16x16x32_bf16 v[30:33], v[50:53], v[30:33], 0
	ds_read_b128 v[50:53], v54 offset:64
	s_waitcnt lgkmcnt(0)
	v_mfma_f32_16x16x32_bf16 v[18:21], v[50:53], v[18:21], v[26:29]
	s_nop 2
	ds_read_b128 v[26:29], v54 offset:128
	s_waitcnt lgkmcnt(0)
	v_mfma_f32_16x16x32_bf16 v[10:13], v[26:29], v[10:13], v[18:21]
	s_nop 2
	ds_read_b128 v[18:21], v54 offset:192
	s_waitcnt lgkmcnt(0)
	v_mfma_f32_16x16x32_bf16 v[2:5], v[18:21], v[2:5], v[10:13]
	s_nop 7
	v_add_f32_e32 v2, v46, v2
	v_mfma_f32_16x16x32_bf16 v[22:25], v[50:53], v[22:25], v[30:33]
	v_mul_f32_e32 v2, 0xbfb8aa3b, v2
	v_exp_f32_e32 v2, v2
	v_mfma_f32_16x16x32_bf16 v[14:17], v[26:29], v[14:17], v[22:25]
	v_add_f32_e32 v2, 1.0, v2
	v_rcp_f32_e32 v2, v2
	v_mfma_f32_16x16x32_bf16 v[12:15], v[18:21], v[6:9], v[14:17]
	v_lshlrev_b32_e32 v6, 1, v45
	v_add3_u32 v7, 0, v48, v6
	v_mul_f32_e32 v2, v2, v49
	v_mul_f32_e32 v2, 0x3fb8aa3b, v2
	v_exp_f32_e32 v18, v2
	s_nop 2
	v_add_f32_e32 v10, v47, v12
	v_mul_f32_e32 v10, 0xbfb8aa3b, v10
	v_exp_f32_e32 v10, v10
	v_mad_u32_u24 v8, v44, s6, v7
	ds_read_u16 v8, v8
	v_fma_f32 v2, -v18, v18, 1.0
	v_add_f32_e32 v10, 1.0, v10
	v_rcp_f32_e32 v10, v10
	v_sqrt_f32_e32 v2, v2
	s_waitcnt lgkmcnt(0)
	v_lshlrev_b32_e32 v9, 16, v8
	v_add3_u32 v6, s41, v48, v6
	v_mul_f32_e32 v9, v10, v9
	v_mul_f32_e32 v11, v9, v2
	v_or_b32_e32 v2, 1, v36
	v_lshl_add_u32 v17, v44, 10, v6
	v_mad_u32_u24 v7, v2, s40, v7
	v_lshl_add_u32 v2, v2, 8, v6
	ds_read_u16 v8, v17
	ds_read_u16 v9, v7
	ds_read_u16 v2, v2
	s_waitcnt lgkmcnt(2)
	v_lshlrev_b32_e32 v8, 16, v8
	s_waitcnt lgkmcnt(1)
	v_lshlrev_b32_e32 v10, 16, v9
	s_waitcnt lgkmcnt(0)
	v_lshlrev_b32_e32 v9, 16, v2
	v_add_f32_e32 v2, v46, v3
	v_mul_f32_e32 v2, 0xbfb8aa3b, v2
	v_exp_f32_e32 v2, v2
	v_add_f32_e32 v3, v47, v13
	v_mul_f32_e32 v3, 0xbfb8aa3b, v3
	v_exp_f32_e32 v3, v3
	v_add_f32_e32 v2, 1.0, v2
	v_rcp_f32_e32 v2, v2
	v_add_f32_e32 v3, 1.0, v3
	v_rcp_f32_e32 v3, v3
	v_mul_f32_e32 v2, v2, v49
	v_mul_f32_e32 v2, 0x3fb8aa3b, v2
	v_exp_f32_e32 v19, v2
	v_mul_f32_e32 v3, v3, v10
	v_fma_f32 v2, -v19, v19, 1.0
	v_sqrt_f32_e32 v2, v2
	s_nop 0
	v_mul_f32_e32 v13, v3, v2
	ds_read_u16 v2, v7 offset:272
	ds_read_u16 v3, v17 offset:512
	s_waitcnt lgkmcnt(1)
	v_lshlrev_b32_e32 v2, 16, v2
	s_waitcnt lgkmcnt(0)
	v_lshlrev_b32_e32 v10, 16, v3
	v_add_f32_e32 v3, v46, v4
	v_mul_f32_e32 v3, 0xbfb8aa3b, v3
	v_exp_f32_e32 v3, v3
	v_add_f32_e32 v4, v47, v14
	v_mul_f32_e32 v4, 0xbfb8aa3b, v4
	v_exp_f32_e32 v4, v4
	v_add_f32_e32 v3, 1.0, v3
	v_rcp_f32_e32 v3, v3
	v_add_f32_e32 v4, 1.0, v4
	v_rcp_f32_e32 v4, v4
	v_mul_f32_e32 v3, v3, v49
	v_mul_f32_e32 v3, 0x3fb8aa3b, v3
	v_exp_f32_e32 v16, v3
	v_mul_f32_e32 v2, v4, v2
	v_add_f32_e32 v4, v47, v15
	v_mul_f32_e32 v4, 0xbfb8aa3b, v4
	v_fma_f32 v3, -v16, v16, 1.0
	v_sqrt_f32_e32 v3, v3
	v_exp_f32_e32 v4, v4
	v_mul_f32_e32 v14, v2, v3
	ds_read_u16 v2, v7 offset:544
	ds_read_u16 v3, v17 offset:768
	v_add_f32_e32 v4, 1.0, v4
	v_rcp_f32_e32 v4, v4
	s_waitcnt lgkmcnt(1)
	v_lshlrev_b32_e32 v2, 16, v2
	s_waitcnt lgkmcnt(0)
	v_lshlrev_b32_e32 v12, 16, v3
	v_add_f32_e32 v3, v46, v5
	v_mul_f32_e32 v3, 0xbfb8aa3b, v3
	v_exp_f32_e32 v3, v3
	v_mul_f32_e32 v2, v4, v2
	v_lshl_add_u64 v[4:5], s[74:75], 0, v[40:41]
	v_add_f32_e32 v3, 1.0, v3
	v_rcp_f32_e32 v3, v3
	s_nop 0
	v_mul_f32_e32 v3, v3, v49
	v_mul_f32_e32 v3, 0x3fb8aa3b, v3
	v_exp_f32_e32 v17, v3
	s_nop 0
	v_fma_f32 v3, -v17, v17, 1.0
	v_sqrt_f32_e32 v3, v3
	s_nop 0
	v_mul_f32_e32 v15, v2, v3
	v_or_b32_e32 v2, s5, v36
	v_ashrrev_i32_e32 v3, 31, v2
	v_lshlrev_b64 v[6:7], 12, v[2:3]
	v_lshl_add_u64 v[20:21], v[4:5], 0, v[6:7]
	s_nop 0
	v_lshl_add_u64 v[6:7], s[90:91], 0, v[6:7]
	v_lshl_add_u64 v[6:7], v[6:7], 0, v[40:41]
	v_add_co_u32_e32 v6, vcc, s42, v6
	s_waitcnt vmcnt(0)
	v_fmac_f32_e32 v11, v72, v18
	v_addc_co_u32_e32 v7, vcc, 0, v7, vcc
	global_store_dword v[6:7], v11, off
	v_or_b32_e32 v6, 1, v2
	v_ashrrev_i32_e32 v7, 31, v6
	v_lshlrev_b64 v[6:7], 12, v[6:7]
	v_lshl_add_u64 v[20:21], v[4:5], 0, v[6:7]
	s_nop 0
	v_lshl_add_u64 v[6:7], s[90:91], 0, v[6:7]
	v_lshl_add_u64 v[6:7], v[6:7], 0, v[40:41]
	v_add_co_u32_e32 v6, vcc, s42, v6
	s_nop 0
	v_fmac_f32_e32 v13, v73, v19
	v_addc_co_u32_e32 v7, vcc, 0, v7, vcc
	global_store_dword v[6:7], v13, off
	v_or_b32_e32 v6, 2, v2
	v_ashrrev_i32_e32 v7, 31, v6
	v_lshlrev_b64 v[6:7], 12, v[6:7]
	v_lshl_add_u64 v[18:19], v[4:5], 0, v[6:7]
	s_nop 0
	v_lshl_add_u64 v[6:7], s[90:91], 0, v[6:7]
	v_lshl_add_u64 v[6:7], v[6:7], 0, v[40:41]
	v_or_b32_e32 v2, 3, v2
	v_add_co_u32_e32 v6, vcc, s42, v6
	s_nop 0
	v_fmac_f32_e32 v14, v74, v16
	v_ashrrev_i32_e32 v3, 31, v2
	v_addc_co_u32_e32 v7, vcc, 0, v7, vcc
	v_lshlrev_b64 v[2:3], 12, v[2:3]
	global_store_dword v[6:7], v14, off
	v_lshl_add_u64 v[4:5], v[4:5], 0, v[2:3]
	s_nop 0
	v_lshl_add_u64 v[2:3], s[90:91], 0, v[2:3]
	v_lshl_add_u64 v[2:3], v[2:3], 0, v[40:41]
	v_add_co_u32_e32 v2, vcc, s42, v2
	s_nop 0
	v_fmac_f32_e32 v15, v75, v17
	v_mul_f32_e32 v4, 0xbfb8aa3b, v8
	v_exp_f32_e32 v4, v4
	v_addc_co_u32_e32 v3, vcc, 0, v3, vcc
	global_store_dword v[2:3], v15, off
	v_add_f32_e32 v4, 1.0, v4
	v_rcp_f32_e32 v8, v4
	v_or_b32_e32 v2, s4, v36
	v_ashrrev_i32_e32 v3, 31, v2
	v_mul_f32_e32 v4, v8, v11
	v_cvt_pk_bf16_f32 v11, v4, v37
	v_lshlrev_b64 v[4:5], 10, v[2:3]
	v_lshl_add_u64 v[4:5], v[4:5], 0, v[38:39]
	v_lshlrev_b64 v[4:5], 1, v[4:5]
	v_lshl_add_u64 v[6:7], s[62:63], 0, v[4:5]
	v_mul_f32_e32 v3, 0, v8
	global_store_short v[6:7], v11, off
	v_cvt_pk_bf16_f32 v3, v3, v37
	v_lshl_add_u64 v[4:5], s[90:91], 0, v[4:5]
	global_store_short v[4:5], v3, off
	v_mul_f32_e32 v3, 0xbfb8aa3b, v9
	v_exp_f32_e32 v3, v3
	v_or_b32_e32 v4, 1, v2
	v_ashrrev_i32_e32 v5, 31, v4
	v_lshlrev_b64 v[4:5], 10, v[4:5]
	v_add_f32_e32 v3, 1.0, v3
	v_rcp_f32_e32 v3, v3
	v_lshl_add_u64 v[4:5], v[4:5], 0, v[38:39]
	v_lshlrev_b64 v[4:5], 1, v[4:5]
	v_mul_f32_e32 v6, v3, v13
	v_cvt_pk_bf16_f32 v8, v6, v37
	v_lshl_add_u64 v[6:7], s[62:63], 0, v[4:5]
	v_mul_f32_e32 v3, 0, v3
	global_store_short v[6:7], v8, off
	v_cvt_pk_bf16_f32 v3, v3, v37
	v_lshl_add_u64 v[4:5], s[90:91], 0, v[4:5]
	global_store_short v[4:5], v3, off
	v_mul_f32_e32 v3, 0xbfb8aa3b, v10
	v_exp_f32_e32 v3, v3
	v_or_b32_e32 v4, 2, v2
	v_ashrrev_i32_e32 v5, 31, v4
	v_lshlrev_b64 v[4:5], 10, v[4:5]
	v_add_f32_e32 v3, 1.0, v3
	v_rcp_f32_e32 v3, v3
	v_lshl_add_u64 v[4:5], v[4:5], 0, v[38:39]
	v_lshlrev_b64 v[4:5], 1, v[4:5]
	v_or_b32_e32 v2, 3, v2
	v_mul_f32_e32 v6, v3, v14
	v_cvt_pk_bf16_f32 v8, v6, v37
	v_lshl_add_u64 v[6:7], s[62:63], 0, v[4:5]
	v_mul_f32_e32 v3, 0, v3
	v_lshl_add_u64 v[4:5], s[90:91], 0, v[4:5]
	global_store_short v[6:7], v8, off
	v_cvt_pk_bf16_f32 v3, v3, v37
	global_store_short v[4:5], v3, off
	v_mul_f32_e32 v4, 0xbfb8aa3b, v12
	v_exp_f32_e32 v4, v4
	v_ashrrev_i32_e32 v3, 31, v2
	v_lshlrev_b64 v[2:3], 10, v[2:3]
	v_lshl_add_u64 v[2:3], v[2:3], 0, v[38:39]
	v_add_f32_e32 v4, 1.0, v4
	v_rcp_f32_e32 v6, v4
	v_lshlrev_b64 v[2:3], 1, v[2:3]
	v_mul_f32_e32 v4, v6, v15
	v_cvt_pk_bf16_f32 v7, v4, v37
	v_lshl_add_u64 v[4:5], s[62:63], 0, v[2:3]
	global_store_short v[4:5], v7, off
	v_mul_f32_e32 v4, 0, v6
	v_lshl_add_u64 v[2:3], s[90:91], 0, v[2:3]
	v_cvt_pk_bf16_f32 v4, v4, v37
	global_store_short v[2:3], v4, off
	s_barrier
	s_cbranch_scc1 .LBB0_535
